# filt_main: split the 64 second-round items across all 512 blocks (8 positions each)
# speedup vs baseline: 1.0426x; 1.0005x over previous
.LBB0_539:
	s_or_b64 exec, exec, s[8:9]
	v_readlane_b32 s0, v254, 57
	s_cmp_lg_u32 s0, 1
	s_cbranch_scc1 .LBB0_555
	v_mov_b32_e32 v0, v176
	s_mov_b32 s4, s94
	s_mov_b32 s100, 0
	s_movk_i32 s101, 64
	s_cmpk_gt_i32 s4, 0x23f
	s_cbranch_scc1 .LBB0_555
	v_readlane_b32 s8, v252, 0
	s_movk_i32 s0, 0x400
	v_ashrrev_i32_e32 v1, 31, v0
	v_readlane_b32 s20, v252, 12
	v_readlane_b32 s21, v252, 13
	v_cmp_gt_i32_e64 s[0:1], s0, v0
	v_add_u32_e32 v10, 0xffffff00, v0
	v_lshlrev_b32_e32 v11, 4, v0
	v_lshl_add_u64 v[2:3], v[0:1], 4, s[20:21]
	v_readlane_b32 s9, v252, 1
	v_readlane_b32 s10, v252, 2
	v_readlane_b32 s11, v252, 3
	v_readlane_b32 s12, v252, 4
	v_readlane_b32 s13, v252, 5
	v_readlane_b32 s14, v252, 6
	v_readlane_b32 s15, v252, 7
	v_readlane_b32 s16, v252, 8
	v_readlane_b32 s17, v252, 9
	v_readlane_b32 s18, v252, 10
	v_readlane_b32 s19, v252, 11
	v_readlane_b32 s22, v252, 14
	v_readlane_b32 s23, v252, 15
	s_branch .LBB0_543
.LBB0_542:
	v_readlane_b32 s2, v254, 41
	s_cmpk_eq_i32 s2, 0x200
	s_cbranch_scc0 .Lfilt_orig
	s_cmpk_ge_i32 s4, 0x200
	v_readlane_b32 s3, v254, 42
	s_cbranch_scc1 .LBB0_555
	s_lshr_b32 s4, s94, 3
	s_addk_i32 s4, 0x200
	s_and_b32 s100, s94, 7
	s_lshl_b32 s100, s100, 3
	s_add_i32 s101, s100, 8
	s_branch .LBB0_543
.Lfilt_orig:
	s_add_i32 s4, s4, s2
	s_cmpk_gt_i32 s4, 0x23f
	v_readlane_b32 s3, v254, 42
	s_cbranch_scc1 .LBB0_555

.LBB0_546:
	s_or_b64 exec, exec, s[10:11]
	v_readlane_b32 s12, v252, 0
	s_and_b64 s[6:7], s[8:9], exec
	s_movk_i32 s5, 0x800
	v_readlane_b32 s20, v252, 8
	v_readlane_b32 s21, v252, 9
	v_readlane_b32 s22, v252, 10
	v_readlane_b32 s23, v252, 11
	s_cselect_b32 s6, s5, 0x100
	s_cselect_b32 s11, s23, s21
	s_cselect_b32 s10, s22, s20
	s_lshl_b32 s5, s4, 8
	s_and_b32 s5, s5, 0xf00
	v_mov_b32_e32 v1, v0
	s_mov_b32 s7, 0x8000
	v_add_u32_e32 v4, s5, v1
	v_ashrrev_i32_e32 v5, 31, v4
	v_lshl_add_u64 v[6:7], v[4:5], 2, s[78:79]
	s_movk_i32 s5, 0x4000
	v_add_co_u32_e32 v8, vcc, s5, v6
	global_load_dword v1, v[6:7], off
	s_nop 0
	v_addc_co_u32_e32 v9, vcc, 0, v7, vcc
	global_load_dword v12, v[8:9], off
	v_add_co_u32_e32 v8, vcc, s7, v6
	s_mov_b32 s7, 0xc000
	s_nop 0
	v_addc_co_u32_e32 v9, vcc, 0, v7, vcc
	global_load_dword v13, v[8:9], off
	v_add_co_u32_e32 v8, vcc, s7, v6
	s_mov_b32 s7, 0x10000
	s_nop 0
	v_addc_co_u32_e32 v9, vcc, 0, v7, vcc
	global_load_dword v14, v[8:9], off
	v_add_co_u32_e32 v8, vcc, s7, v6
	s_mov_b32 s7, 0x14000
	s_nop 0
	v_addc_co_u32_e32 v9, vcc, 0, v7, vcc
	global_load_dword v15, v[8:9], off
	v_add_co_u32_e32 v8, vcc, s7, v6
	s_mov_b32 s7, 0x18000
	s_nop 0
	v_addc_co_u32_e32 v9, vcc, 0, v7, vcc
	global_load_dword v16, v[8:9], off
	v_add_co_u32_e32 v8, vcc, s7, v6
	s_mov_b32 s7, 0x1c000
	s_nop 0
	v_addc_co_u32_e32 v9, vcc, 0, v7, vcc
	global_load_dword v17, v[8:9], off
	v_add_co_u32_e32 v8, vcc, s7, v6
	s_mov_b32 s7, 0x20000
	s_nop 0
	v_addc_co_u32_e32 v9, vcc, 0, v7, vcc
	global_load_dword v18, v[8:9], off
	v_add_co_u32_e32 v8, vcc, s7, v6
	s_mov_b32 s7, 0x24000
	s_nop 0
	v_addc_co_u32_e32 v9, vcc, 0, v7, vcc
	global_load_dword v19, v[8:9], off
	v_add_co_u32_e32 v8, vcc, s7, v6
	s_mov_b32 s7, 0x28000
	s_nop 0
	v_addc_co_u32_e32 v9, vcc, 0, v7, vcc
	global_load_dword v20, v[8:9], off
	v_add_co_u32_e32 v8, vcc, s7, v6
	s_mov_b32 s7, 0x2c000
	s_nop 0
	v_addc_co_u32_e32 v9, vcc, 0, v7, vcc
	global_load_dword v21, v[8:9], off
	v_add_co_u32_e32 v8, vcc, s7, v6
	s_mov_b32 s7, 0x30000
	s_nop 0
	v_addc_co_u32_e32 v9, vcc, 0, v7, vcc
	global_load_dword v22, v[8:9], off
	v_add_co_u32_e32 v8, vcc, s7, v6
	s_mov_b32 s7, 0x34000
	s_nop 0
	v_addc_co_u32_e32 v9, vcc, 0, v7, vcc
	global_load_dword v23, v[8:9], off
	v_add_co_u32_e32 v8, vcc, s7, v6
	s_mov_b32 s7, 0x38000
	s_nop 0
	v_addc_co_u32_e32 v9, vcc, 0, v7, vcc
	global_load_dword v24, v[8:9], off
	v_add_co_u32_e32 v8, vcc, s7, v6
	s_mov_b32 s7, 0x3c000
	s_nop 0
	v_addc_co_u32_e32 v9, vcc, 0, v7, vcc
	global_load_dword v25, v[8:9], off
	v_add_co_u32_e32 v8, vcc, s7, v6
	s_mov_b32 s7, 0x40000
	s_nop 0
	v_addc_co_u32_e32 v9, vcc, 0, v7, vcc
	global_load_dword v26, v[8:9], off
	v_add_co_u32_e32 v8, vcc, s7, v6
	s_mov_b32 s7, 0x44000
	s_nop 0
	v_addc_co_u32_e32 v9, vcc, 0, v7, vcc
	global_load_dword v27, v[8:9], off
	v_add_co_u32_e32 v8, vcc, s7, v6
	s_mov_b32 s7, 0x48000
	s_nop 0
	v_addc_co_u32_e32 v9, vcc, 0, v7, vcc
	global_load_dword v28, v[8:9], off
	v_add_co_u32_e32 v8, vcc, s7, v6
	s_mov_b32 s7, 0x4c000
	s_nop 0
	v_addc_co_u32_e32 v9, vcc, 0, v7, vcc
	global_load_dword v29, v[8:9], off
	v_add_co_u32_e32 v8, vcc, s7, v6
	s_mov_b32 s7, 0x50000
	s_nop 0
	v_addc_co_u32_e32 v9, vcc, 0, v7, vcc
	global_load_dword v30, v[8:9], off
	v_add_co_u32_e32 v8, vcc, s7, v6
	s_mov_b32 s7, 0x54000
	s_nop 0
	v_addc_co_u32_e32 v9, vcc, 0, v7, vcc
	global_load_dword v31, v[8:9], off
	v_add_co_u32_e32 v8, vcc, s7, v6
	s_mov_b32 s7, 0x58000
	s_nop 0
	v_addc_co_u32_e32 v9, vcc, 0, v7, vcc
	global_load_dword v32, v[8:9], off
	v_add_co_u32_e32 v8, vcc, s7, v6
	s_mov_b32 s7, 0x5c000
	s_nop 0
	v_addc_co_u32_e32 v9, vcc, 0, v7, vcc
	global_load_dword v33, v[8:9], off
	v_add_co_u32_e32 v8, vcc, s7, v6
	s_mov_b32 s7, 0x60000
	s_nop 0
	v_addc_co_u32_e32 v9, vcc, 0, v7, vcc
	global_load_dword v34, v[8:9], off
	v_add_co_u32_e32 v8, vcc, s7, v6
	s_mov_b32 s7, 0x64000
	s_nop 0
	v_addc_co_u32_e32 v9, vcc, 0, v7, vcc
	global_load_dword v35, v[8:9], off
	v_add_co_u32_e32 v8, vcc, s7, v6
	s_mov_b32 s7, 0x68000
	s_nop 0
	v_addc_co_u32_e32 v9, vcc, 0, v7, vcc
	global_load_dword v36, v[8:9], off
	v_add_co_u32_e32 v8, vcc, s7, v6
	s_mov_b32 s7, 0x6c000
	s_nop 0
	v_addc_co_u32_e32 v9, vcc, 0, v7, vcc
	global_load_dword v37, v[8:9], off
	v_add_co_u32_e32 v8, vcc, s7, v6
	s_mov_b32 s7, 0x70000
	s_nop 0
	v_addc_co_u32_e32 v9, vcc, 0, v7, vcc
	global_load_dword v38, v[8:9], off
	v_add_co_u32_e32 v8, vcc, s7, v6
	s_mov_b32 s7, 0x74000
	s_nop 0
	v_addc_co_u32_e32 v9, vcc, 0, v7, vcc
	global_load_dword v39, v[8:9], off
	v_add_co_u32_e32 v8, vcc, s7, v6
	s_mov_b32 s7, 0x78000
	s_nop 0
	v_addc_co_u32_e32 v9, vcc, 0, v7, vcc
	global_load_dword v40, v[8:9], off
	v_add_co_u32_e32 v8, vcc, s7, v6
	s_mov_b32 s7, 0x7c000
	s_nop 0
	v_addc_co_u32_e32 v9, vcc, 0, v7, vcc
	global_load_dword v41, v[8:9], off
	v_add_co_u32_e32 v8, vcc, s7, v6
	s_mov_b32 s7, 0x80000
	s_nop 0
	v_addc_co_u32_e32 v9, vcc, 0, v7, vcc
	global_load_dword v42, v[8:9], off
	v_add_co_u32_e32 v8, vcc, s7, v6
	s_mov_b32 s7, 0x84000
	s_nop 0
	v_addc_co_u32_e32 v9, vcc, 0, v7, vcc
	global_load_dword v43, v[8:9], off
	v_add_co_u32_e32 v8, vcc, s7, v6
	s_mov_b32 s7, 0x88000
	s_nop 0
	v_addc_co_u32_e32 v9, vcc, 0, v7, vcc
	global_load_dword v44, v[8:9], off
	v_add_co_u32_e32 v8, vcc, s7, v6
	s_mov_b32 s7, 0x8c000
	s_nop 0
	v_addc_co_u32_e32 v9, vcc, 0, v7, vcc
	global_load_dword v45, v[8:9], off
	v_add_co_u32_e32 v8, vcc, s7, v6
	s_mov_b32 s7, 0x90000
	s_nop 0
	v_addc_co_u32_e32 v9, vcc, 0, v7, vcc
	global_load_dword v46, v[8:9], off
	v_add_co_u32_e32 v8, vcc, s7, v6
	s_mov_b32 s7, 0x94000
	s_nop 0
	v_addc_co_u32_e32 v9, vcc, 0, v7, vcc
	global_load_dword v47, v[8:9], off
	v_add_co_u32_e32 v8, vcc, s7, v6
	s_mov_b32 s7, 0x98000
	s_nop 0
	v_addc_co_u32_e32 v9, vcc, 0, v7, vcc
	global_load_dword v48, v[8:9], off
	v_add_co_u32_e32 v8, vcc, s7, v6
	s_mov_b32 s7, 0x9c000
	s_nop 0
	v_addc_co_u32_e32 v9, vcc, 0, v7, vcc
	global_load_dword v49, v[8:9], off
	v_add_co_u32_e32 v8, vcc, s7, v6
	s_mov_b32 s7, 0xa0000
	s_nop 0
	v_addc_co_u32_e32 v9, vcc, 0, v7, vcc
	global_load_dword v50, v[8:9], off
	v_add_co_u32_e32 v8, vcc, s7, v6
	s_mov_b32 s7, 0xa4000
	s_nop 0
	v_addc_co_u32_e32 v9, vcc, 0, v7, vcc
	global_load_dword v51, v[8:9], off
	v_add_co_u32_e32 v8, vcc, s7, v6
	s_mov_b32 s7, 0xa8000
	s_nop 0
	v_addc_co_u32_e32 v9, vcc, 0, v7, vcc
	global_load_dword v52, v[8:9], off
	v_add_co_u32_e32 v8, vcc, s7, v6
	s_mov_b32 s7, 0xac000
	s_nop 0
	v_addc_co_u32_e32 v9, vcc, 0, v7, vcc
	global_load_dword v53, v[8:9], off
	v_add_co_u32_e32 v8, vcc, s7, v6
	s_mov_b32 s7, 0xb0000
	s_nop 0
	v_addc_co_u32_e32 v9, vcc, 0, v7, vcc
	global_load_dword v54, v[8:9], off
	v_add_co_u32_e32 v8, vcc, s7, v6
	s_mov_b32 s7, 0xb4000
	s_nop 0
	v_addc_co_u32_e32 v9, vcc, 0, v7, vcc
	global_load_dword v55, v[8:9], off
	v_add_co_u32_e32 v8, vcc, s7, v6
	s_mov_b32 s7, 0xb8000
	s_nop 0
	v_addc_co_u32_e32 v9, vcc, 0, v7, vcc
	global_load_dword v56, v[8:9], off
	v_add_co_u32_e32 v8, vcc, s7, v6
	s_mov_b32 s7, 0xbc000
	s_nop 0
	v_addc_co_u32_e32 v9, vcc, 0, v7, vcc
	global_load_dword v57, v[8:9], off
	v_add_co_u32_e32 v8, vcc, s7, v6
	s_mov_b32 s7, 0xc0000
	s_nop 0
	v_addc_co_u32_e32 v9, vcc, 0, v7, vcc
	global_load_dword v58, v[8:9], off
	v_add_co_u32_e32 v8, vcc, s7, v6
	s_mov_b32 s7, 0xc4000
	s_nop 0
	v_addc_co_u32_e32 v9, vcc, 0, v7, vcc
	global_load_dword v59, v[8:9], off
	v_add_co_u32_e32 v8, vcc, s7, v6
	s_mov_b32 s7, 0xc8000
	s_nop 0
	v_addc_co_u32_e32 v9, vcc, 0, v7, vcc
	global_load_dword v60, v[8:9], off
	v_add_co_u32_e32 v8, vcc, s7, v6
	s_mov_b32 s7, 0xcc000
	s_nop 0
	v_addc_co_u32_e32 v9, vcc, 0, v7, vcc
	global_load_dword v61, v[8:9], off
	v_add_co_u32_e32 v8, vcc, s7, v6
	s_mov_b32 s7, 0xd0000
	s_nop 0
	v_addc_co_u32_e32 v9, vcc, 0, v7, vcc
	global_load_dword v62, v[8:9], off
	v_add_co_u32_e32 v8, vcc, s7, v6
	s_mov_b32 s7, 0xd4000
	s_nop 0
	v_addc_co_u32_e32 v9, vcc, 0, v7, vcc
	global_load_dword v63, v[8:9], off
	v_add_co_u32_e32 v8, vcc, s7, v6
	s_mov_b32 s7, 0xd8000
	s_nop 0
	v_addc_co_u32_e32 v9, vcc, 0, v7, vcc
	global_load_dword v64, v[8:9], off
	v_add_co_u32_e32 v8, vcc, s7, v6
	s_mov_b32 s7, 0xdc000
	s_nop 0
	v_addc_co_u32_e32 v9, vcc, 0, v7, vcc
	global_load_dword v66, v[8:9], off
	v_add_co_u32_e32 v8, vcc, s7, v6
	s_mov_b32 s7, 0xe0000
	s_nop 0
	v_addc_co_u32_e32 v9, vcc, 0, v7, vcc
	global_load_dword v67, v[8:9], off
	v_add_co_u32_e32 v8, vcc, s7, v6
	s_mov_b32 s7, 0xe4000
	s_nop 0
	v_addc_co_u32_e32 v9, vcc, 0, v7, vcc
	global_load_dword v68, v[8:9], off
	v_add_co_u32_e32 v8, vcc, s7, v6
	s_mov_b32 s7, 0xe8000
	s_nop 0
	v_addc_co_u32_e32 v9, vcc, 0, v7, vcc
	global_load_dword v69, v[8:9], off
	v_add_co_u32_e32 v8, vcc, s7, v6
	s_mov_b32 s7, 0xec000
	s_nop 0
	v_addc_co_u32_e32 v9, vcc, 0, v7, vcc
	global_load_dword v70, v[8:9], off
	v_add_co_u32_e32 v8, vcc, s7, v6
	s_mov_b32 s7, 0xf0000
	s_nop 0
	v_addc_co_u32_e32 v9, vcc, 0, v7, vcc
	global_load_dword v71, v[8:9], off
	v_add_co_u32_e32 v8, vcc, s7, v6
	s_mov_b32 s7, 0xf4000
	s_nop 0
	v_addc_co_u32_e32 v9, vcc, 0, v7, vcc
	global_load_dword v72, v[8:9], off
	v_add_co_u32_e32 v8, vcc, s7, v6
	s_mov_b32 s7, 0xf8000
	s_nop 0
	v_addc_co_u32_e32 v9, vcc, 0, v7, vcc
	global_load_dword v73, v[8:9], off
	v_add_co_u32_e32 v8, vcc, s7, v6
	s_mov_b32 s7, 0xfc000
	s_nop 0
	v_addc_co_u32_e32 v9, vcc, 0, v7, vcc
	v_add_co_u32_e32 v6, vcc, s7, v6
	global_load_dword v74, v[8:9], off
	s_nop 0
	v_addc_co_u32_e32 v7, vcc, 0, v7, vcc
	global_load_dword v75, v[6:7], off
	v_and_b32_e32 v5, 0x3ff, v4
	v_cvt_f32_u32_e32 v5, v5
	v_mov_b32_e32 v6, 0xc0447cbd
	s_movk_i32 s7, 0xfc00
	s_lshl_b32 s76, s6, 1
	v_fmamk_f32 v76, v5, 0xbc44ade8, v6
	v_ashrrev_i32_e32 v5, 1, v4
	v_bfi_b32 v6, s7, v5, v4
	s_and_b64 s[8:9], s[8:9], exec
	v_ashrrev_i32_e32 v7, 31, v6
	s_cselect_b32 s7, 12, 9
	v_lshlrev_b64 v[6:7], s7, v[6:7]
	v_lshlrev_b64 v[8:9], 1, v[6:7]
	v_lshl_add_u64 v[6:7], s[10:11], 0, v[8:9]
	s_add_i32 s7, s6, -1
	v_and_b32_e32 v4, 0x400, v4
	s_lshl_b32 s8, s6, 2
	s_mov_b32 s9, s77
	v_cmp_ne_u32_e64 s[36:37], 0, v4
	v_lshl_add_u64 v[4:5], v[6:7], 0, s[8:9]
	s_add_u32 s8, s10, -2
	s_addc_u32 s9, s11, -1
	s_lshl_b64 s[10:11], s[2:3], 1
	s_add_u32 s6, s2, s6
	v_cvt_f32_u32_e32 v77, s7
	s_addc_u32 s7, s3, 0
	v_lshl_add_u64 v[6:7], v[8:9], 0, s[76:77]
	s_lshl_b64 s[6:7], s[6:7], 1
	v_subrev_co_u32_e32 v6, vcc, s10, v6
	v_mov_b32_e32 v78, s11
	s_add_u32 s6, s8, s6
	v_subb_co_u32_e32 v7, vcc, v7, v78, vcc
	s_addc_u32 s7, s9, s7
	s_mov_b32 s5, 0
	v_lshl_add_u64 v[6:7], s[8:9], 0, v[6:7]
	v_lshl_add_u64 v[8:9], s[6:7], 0, v[8:9]
	s_mov_b32 s3, 0
	s_movk_i32 s76, 0x5000
	v_readlane_b32 s13, v252, 1
	v_readlane_b32 s14, v252, 2
	v_readlane_b32 s15, v252, 3
	v_readlane_b32 s16, v252, 4
	v_readlane_b32 s17, v252, 5
	v_readlane_b32 s18, v252, 6
	v_readlane_b32 s19, v252, 7
	v_readlane_b32 s24, v252, 12
	v_readlane_b32 s25, v252, 13
	v_readlane_b32 s26, v252, 14
	v_readlane_b32 s27, v252, 15
	s_waitcnt lgkmcnt(0)
	s_barrier
	s_waitcnt vmcnt(0)
	s_mov_b32 s3, s100
	s_lshl_b32 s5, s100, 8
	v_mov_b32_e32 v96, s100
	v_mov_b32_e32 v97, 0
	v_lshl_add_u64 v[8:9], v[96:97], 1, v[8:9]
	v_sub_u32_e32 v96, 0, v96
	v_ashrrev_i32_e32 v97, 31, v96
	v_lshl_add_u64 v[6:7], v[96:97], 1, v[6:7]
	s_branch .LBB0_548
.LBB0_547:
	s_or_b64 exec, exec, s[8:9]
	s_add_i32 s3, s3, 1
	s_addk_i32 s5, 0x100
	v_lshl_add_u64 v[6:7], v[6:7], 0, -2
	s_cmp_eq_u32 s3, s101
	v_lshl_add_u64 v[8:9], v[8:9], 0, 2
	s_cbranch_scc1 .LBB0_542
